# GEMM tile prologue: accumulators zeroed with 64 v_mov_b64 instead of 128 v_mov_b32
# speedup vs baseline: 1.0115x; 1.0009x over previous
; template <class Epi, class Sched, bool ALIGN_EPI = false, bool SP2 = false>
; __device__ __forceinline__ void gemm_phase(PG8_LAS unsigned char* lds, const Gemm g, const Sched& S, const Epi& E) {
;     ...
; #pragma unroll
;         for (int a = 0; a < 2; ++a)
; #pragma unroll
;             for (int b = 0; b < 2; ++b)
; #pragma unroll
;                 for (int m = 0; m < 4; ++m)
; #pragma unroll
;                     for (int n = 0; n < 2; ++n) acc[a][b][m][n] = (f32x4){0.f, 0.f, 0.f, 0.f};
;         cur = nxt; cA = nA; cB = nB; ++ui;
.LBB0_58:
	s_add_u32 s4, s38, 0x80
	s_addc_u32 s5, s39, 0
	s_add_u32 s20, s34, 0x100
	s_addc_u32 s38, s35, 0
	s_mov_b32 s34, 0
	v_mov_b64_e32 v[2:3], 0
	v_mov_b64_e32 v[4:5], 0
	v_mov_b64_e32 v[6:7], 0
	v_mov_b64_e32 v[8:9], 0
	v_mov_b64_e32 v[10:11], 0
	v_mov_b64_e32 v[12:13], 0
	v_mov_b64_e32 v[14:15], 0
	v_mov_b64_e32 v[16:17], 0
	v_mov_b64_e32 v[18:19], 0
	v_mov_b64_e32 v[20:21], 0
	v_mov_b64_e32 v[22:23], 0
	v_mov_b64_e32 v[24:25], 0
	v_mov_b64_e32 v[26:27], 0
	v_mov_b64_e32 v[28:29], 0
	v_mov_b64_e32 v[30:31], 0
	v_mov_b64_e32 v[32:33], 0
	v_mov_b64_e32 v[34:35], 0
	v_mov_b64_e32 v[36:37], 0
	v_mov_b64_e32 v[38:39], 0
	v_mov_b64_e32 v[40:41], 0
	v_mov_b64_e32 v[42:43], 0
	v_mov_b64_e32 v[44:45], 0
	v_mov_b64_e32 v[46:47], 0
	v_mov_b64_e32 v[48:49], 0
	v_mov_b64_e32 v[50:51], 0
	v_mov_b64_e32 v[52:53], 0
	v_mov_b64_e32 v[54:55], 0
	v_mov_b64_e32 v[56:57], 0
	v_mov_b64_e32 v[58:59], 0
	v_mov_b64_e32 v[60:61], 0
	v_mov_b64_e32 v[62:63], 0
	v_mov_b64_e32 v[64:65], 0
	v_mov_b64_e32 v[66:67], 0
	v_mov_b64_e32 v[68:69], 0
	v_mov_b64_e32 v[70:71], 0
	v_mov_b64_e32 v[72:73], 0
	v_mov_b64_e32 v[74:75], 0
	v_mov_b64_e32 v[76:77], 0
	v_mov_b64_e32 v[78:79], 0
	v_mov_b64_e32 v[80:81], 0
	v_mov_b64_e32 v[82:83], 0
	v_mov_b64_e32 v[84:85], 0
	v_mov_b64_e32 v[86:87], 0
	v_mov_b64_e32 v[88:89], 0
	v_mov_b64_e32 v[90:91], 0
	v_mov_b64_e32 v[92:93], 0
	v_mov_b64_e32 v[94:95], 0
	v_mov_b64_e32 v[96:97], 0
	v_mov_b64_e32 v[98:99], 0
	v_mov_b64_e32 v[100:101], 0
	v_mov_b64_e32 v[102:103], 0
	v_mov_b64_e32 v[104:105], 0
	v_mov_b64_e32 v[106:107], 0
	v_mov_b64_e32 v[108:109], 0
	s_waitcnt vmcnt(0)
	v_mov_b64_e32 v[110:111], 0
	v_mov_b64_e32 v[112:113], 0
	v_mov_b64_e32 v[114:115], 0
	v_mov_b64_e32 v[116:117], 0
	v_mov_b64_e32 v[118:119], 0
	v_mov_b64_e32 v[120:121], 0
	v_mov_b64_e32 v[122:123], 0
	v_mov_b64_e32 v[124:125], 0
	v_mov_b64_e32 v[126:127], 0
	v_mov_b64_e32 v[128:129], 0
